# micro-opts: acc zeroing with v_mov_b64, NSA ones operand kept in registers, layer-0 norm wave-sum by DPP
# baseline (speedup 1.0000x reference)
; DI float wave_sum(float v, int lane) {
; #pragma unroll
;   for (int o = 32; o > 0; o >>= 1) v += shx(v, o, lane);
;   return v;
; }
; DI void norm_phase(const float* xin, const float* g, bf16_t* h) {
;     ...
;   for (int row = gw; row < T_TOK; row += nw) {
;     const float4* xr = (const float4*)(xin + (size_t)row * DM);
;     float4 v[4];
;     float ss = 0.f;
; #pragma unroll
;     for (int i = 0; i < 4; ++i) {
;       v[i] = xr[i * 64 + lane];
;       ss += v[i].x * v[i].x + v[i].y * v[i].y + v[i].z * v[i].z + v[i].w * v[i].w;
;     }
;     ss = wave_sum(ss, lane);
;     float rs = rsqrtf(ss * (1.f / 1024.f) + 1e-6f);
;     uint2* hr = (uint2*)(h + (size_t)row * DM);
; #pragma unroll
;     for (int i = 0; i < 4; ++i) {
;       uint2 o;
;       o.x = pack2(v[i].x * rs * gv[i].x, v[i].y * rs * gv[i].y);
;       o.y = pack2(v[i].z * rs * gv[i].z, v[i].w * rs * gv[i].w);
;       hr[i * 64 + lane] = o;
;     }
.LBB0_74:
	global_load_dwordx4 v[30:33], v[22:23], off offset:-2048
	global_load_dwordx4 v[34:37], v[22:23], off offset:-1024
	global_load_dwordx4 v[38:41], v[22:23], off
	global_load_dwordx4 v[42:45], v[22:23], off offset:1024
	v_add_u32_e32 v18, s10, v18
	s_movk_i32 s5, 0x7fff
	v_cmp_lt_i32_e32 vcc, s5, v18
	s_or_b64 s[6:7], vcc, s[6:7]
	v_lshl_add_u64 v[22:23], v[22:23], 0, s[20:21]
	s_waitcnt vmcnt(3)
	v_mov_b32_e32 v52, v31
	s_waitcnt vmcnt(2)
	v_mov_b32_e32 v53, v35
	v_mov_b32_e32 v50, v30
	v_mov_b32_e32 v51, v34
	s_waitcnt vmcnt(1)
	v_mov_b32_e32 v60, v39
	s_waitcnt vmcnt(0)
	v_mov_b32_e32 v61, v43
	v_pk_mul_f32 v[52:53], v[52:53], v[52:53]
	v_mov_b32_e32 v46, v32
	v_mov_b32_e32 v47, v36
	v_mov_b32_e32 v58, v38
	v_mov_b32_e32 v59, v42
	v_pk_mul_f32 v[60:61], v[60:61], v[60:61]
	v_pk_fma_f32 v[50:51], v[50:51], v[50:51], v[52:53]
	v_mov_b32_e32 v48, v33
	v_mov_b32_e32 v49, v37
	v_mov_b32_e32 v54, v40
	v_mov_b32_e32 v55, v44
	v_pk_fma_f32 v[52:53], v[58:59], v[58:59], v[60:61]
	v_pk_fma_f32 v[46:47], v[46:47], v[46:47], v[50:51]
	v_mov_b32_e32 v56, v41
	v_mov_b32_e32 v57, v45
	v_pk_fma_f32 v[50:51], v[54:55], v[54:55], v[52:53]
	v_pk_fma_f32 v[46:47], v[48:49], v[48:49], v[46:47]
	v_pk_fma_f32 v[48:49], v[56:57], v[56:57], v[50:51]
	v_add_f32_e32 v19, v46, v47
	v_add_f32_e32 v19, v19, v48
	v_add_f32_e32 v19, v19, v49
	s_nop 1
	v_add_f32_dpp v19, v19, v19 quad_perm:[1,0,3,2] row_mask:0xf bank_mask:0xf
	s_nop 1
	v_add_f32_dpp v19, v19, v19 quad_perm:[2,3,0,1] row_mask:0xf bank_mask:0xf
	s_nop 1
	v_add_f32_dpp v19, v19, v19 row_half_mirror row_mask:0xf bank_mask:0xf
	s_nop 1
	v_add_f32_dpp v19, v19, v19 row_mirror row_mask:0xf bank_mask:0xf
	s_nop 1
	v_add_f32_dpp v19, v19, v19 row_bcast:15 row_mask:0xa bank_mask:0xf
	s_nop 1
	v_add_f32_dpp v19, v19, v19 row_bcast:31 row_mask:0xc bank_mask:0xf
	s_nop 1
	v_readlane_b32 s98, v19, 63
	s_nop 1
	v_mov_b32_e32 v19, s98
	v_fmamk_f32 v19, v19, 0x3a800000, v62
	v_mul_f32_e32 v29, 0x4b800000, v19
	v_cmp_gt_f32_e32 vcc, s9, v19
	s_nop 1
	v_cndmask_b32_e32 v19, v19, v29, vcc
	v_rsq_f32_e32 v19, v19
	s_nop 0
	v_mul_f32_e32 v29, 0x45800000, v19
	v_cndmask_b32_e32 v46, v19, v29, vcc
	v_pk_mul_f32 v[30:31], v[30:31], v[46:47] op_sel_hi:[1,0]
	v_pk_mul_f32 v[32:33], v[32:33], v[46:47] op_sel_hi:[1,0]
	v_pk_mul_f32 v[34:35], v[34:35], v[46:47] op_sel_hi:[1,0]
	v_pk_mul_f32 v[36:37], v[36:37], v[46:47] op_sel_hi:[1,0]
	v_pk_mul_f32 v[38:39], v[38:39], v[46:47] op_sel_hi:[1,0]
	v_pk_mul_f32 v[40:41], v[40:41], v[46:47] op_sel_hi:[1,0]
	v_pk_mul_f32 v[42:43], v[42:43], v[46:47] op_sel_hi:[1,0]
	v_pk_mul_f32 v[44:45], v[44:45], v[46:47] op_sel_hi:[1,0]
	v_pk_mul_f32 v[30:31], v[2:3], v[30:31]
	v_pk_mul_f32 v[32:33], v[4:5], v[32:33]
	v_pk_mul_f32 v[34:35], v[6:7], v[34:35]
	v_pk_mul_f32 v[36:37], v[8:9], v[36:37]
	v_pk_mul_f32 v[38:39], v[10:11], v[38:39]
	v_pk_mul_f32 v[40:41], v[12:13], v[40:41]
	v_pk_mul_f32 v[42:43], v[14:15], v[42:43]
	v_pk_mul_f32 v[44:45], v[16:17], v[44:45]
	v_cvt_pk_bf16_f32 v30, v30, v31
	v_cvt_pk_bf16_f32 v31, v32, v33
	v_cvt_pk_bf16_f32 v32, v34, v35
	v_cvt_pk_bf16_f32 v33, v36, v37
	v_cvt_pk_bf16_f32 v34, v38, v39
	v_cvt_pk_bf16_f32 v35, v40, v41
	v_cvt_pk_bf16_f32 v36, v42, v43
	v_cvt_pk_bf16_f32 v37, v44, v45
	global_store_dwordx2 v[20:21], v[30:31], off
	global_store_dwordx2 v[20:21], v[32:33], off offset:512
	global_store_dwordx2 v[20:21], v[34:35], off offset:1024
	global_store_dwordx2 v[20:21], v[36:37], off offset:1536
	v_lshl_add_u64 v[20:21], v[20:21], 0, s[12:13]
	s_andn2_b64 exec, exec, s[6:7]
	s_cbranch_execnz .LBB0_74

; DI void zero_acc8(f32x4 (&acc)[8][4]) {
; #pragma unroll
;   for (int i = 0; i < 8; ++i)
; #pragma unroll
;     for (int j = 0; j < 4; ++j) acc[i][j] = f32x4{0.f, 0.f, 0.f, 0.f};
; }
; __global__ void __launch_bounds__(512, 2) mega(Params p) {
;     ...
;     GEMM8_TILE_LOOP(22) {
;       const int m0 = mt * 256, n0 = ntile * 256;
;       f32x4 acc8[8][4];
;       zero_acc8(acc8);
;       gemm8_accum(acc8, hbuf + (size_t)m0 * DM, DM, wl + W_IN + (size_t)n0 * 1024, 1024, 16, lds_all, !first_,
;                   hbuf + (size_t)mtn * 256 * DM, DM, wl + W_IN + (size_t)ntilen * 256 * 1024, 1024);
.LBB0_133:
	v_lshlrev_b64 v[40:41], 1, v[168:169]
	v_lshlrev_b64 v[42:43], 1, v[166:167]
	v_lshl_add_u64 v[6:7], s[2:3], 0, v[40:41]
	v_lshl_add_u64 v[8:9], s[2:3], 0, v[42:43]
	v_lshlrev_b64 v[44:45], 1, v[0:1]
	global_load_dwordx4 v[18:21], v[6:7], off offset:128
	global_load_dwordx4 v[26:29], v[8:9], off offset:128
	v_lshl_add_u64 v[10:11], s[2:3], 0, v[44:45]
	global_load_dwordx4 v[22:25], v[4:5], off offset:128
	global_load_dwordx4 v[30:33], v[10:11], off offset:128
	global_load_dwordx4 v[6:9], v[2:3], off offset:128
	v_lshl_add_u64 v[2:3], s[0:1], 0, v[40:41]
	s_nop 1
	global_load_dwordx4 v[2:5], v[2:3], off offset:128
	v_lshl_add_u64 v[10:11], s[0:1], 0, v[42:43]
	v_lshl_add_u64 v[14:15], s[0:1], 0, v[44:45]
	global_load_dwordx4 v[10:13], v[10:11], off offset:128
	s_nop 0
	global_load_dwordx4 v[14:17], v[14:15], off offset:128
	v_bfe_u32 v39, v36, 4, 2
	v_lshrrev_b32_e32 v46, 1, v36
	v_bitop3_b32 v46, v46, v39, 7 bitop3:0x6c
	v_lshlrev_b32_e32 v191, 3, v46
	v_lshlrev_b32_e32 v46, 5, v36
	v_bfe_u32 v47, v36, 1, 3
	v_and_b32_e32 v46, 0xffffe000, v46
	v_lshlrev_b32_e32 v36, 6, v36
	s_movk_i32 s0, 0x3c0
	v_and_or_b32 v46, v36, s0, v46
	s_add_u32 s0, s39, s13
	v_add_u32_e32 v34, v35, v34
	v_mov_b32_e32 v35, v1
	s_addc_u32 s1, s40, 0
	v_lshlrev_b64 v[34:35], 1, v[34:35]
	v_lshl_add_u64 v[170:171], s[0:1], 0, v[44:45]
	v_lshl_add_u64 v[172:173], s[0:1], 0, v[42:43]
	v_lshl_add_u64 v[174:175], s[0:1], 0, v[40:41]
	v_lshl_add_u64 v[176:177], s[0:1], 0, v[34:35]
	s_add_i32 s0, s38, s11
	s_add_i32 s0, s0, s12
	s_lshl_b32 s0, s0, 19
	v_readlane_b32 s1, v253, 57
	s_add_u32 s0, s1, s0
	v_readlane_b32 s1, v253, 58
	s_addc_u32 s1, s1, 0
	v_and_b32_e32 v36, 0x33c0, v36
	v_bitop3_b32 v39, v39, v47, 4 bitop3:0x36
	v_lshlrev_b32_e32 v189, 1, v38
	v_lshlrev_b32_e32 v190, 1, v37
	v_lshl_add_u64 v[184:185], s[0:1], 0, v[34:35]
	v_mov_b32_e32 v34, 0
	v_lshlrev_b32_e32 v188, 3, v39
	v_add3_u32 v163, 0, v189, v190
	v_lshl_add_u64 v[178:179], s[0:1], 0, v[44:45]
	v_lshl_add_u64 v[180:181], s[0:1], 0, v[42:43]
	v_lshl_add_u64 v[182:183], s[0:1], 0, v[40:41]
	s_mov_b64 s[0:1], 0
	s_mov_b32 s2, 0
	v_lshlrev_b32_e32 v187, 1, v46
	v_lshlrev_b32_e32 v186, 1, v36
	v_mov_b32_e32 v35, v34
	v_mov_b64_e32 v[36:37], v[34:35]
	v_mov_b64_e32 v[38:39], v[34:35]
	v_mov_b64_e32 v[40:41], v[34:35]
	v_mov_b64_e32 v[42:43], v[34:35]
	v_mov_b64_e32 v[44:45], v[34:35]
	v_mov_b64_e32 v[46:47], v[34:35]
	v_mov_b64_e32 v[48:49], v[34:35]
	v_mov_b64_e32 v[50:51], v[34:35]
	v_mov_b64_e32 v[52:53], v[34:35]
	v_mov_b64_e32 v[54:55], v[34:35]
	v_mov_b64_e32 v[56:57], v[34:35]
	v_mov_b64_e32 v[58:59], v[34:35]
	v_mov_b64_e32 v[60:61], v[34:35]
	v_mov_b64_e32 v[62:63], v[34:35]
	v_mov_b64_e32 v[64:65], v[34:35]
	v_mov_b64_e32 v[66:67], v[34:35]
	v_mov_b64_e32 v[68:69], v[34:35]
	v_mov_b64_e32 v[70:71], v[34:35]
	v_mov_b64_e32 v[72:73], v[34:35]
	v_mov_b64_e32 v[74:75], v[34:35]
	v_mov_b64_e32 v[76:77], v[34:35]
	v_mov_b64_e32 v[78:79], v[34:35]
	v_mov_b64_e32 v[80:81], v[34:35]
	v_mov_b64_e32 v[82:83], v[34:35]
	v_mov_b64_e32 v[84:85], v[34:35]
	v_mov_b64_e32 v[86:87], v[34:35]
	v_mov_b64_e32 v[88:89], v[34:35]
	v_mov_b64_e32 v[90:91], v[34:35]
	v_mov_b64_e32 v[92:93], v[34:35]
	v_mov_b64_e32 v[94:95], v[34:35]
	v_mov_b64_e32 v[96:97], v[34:35]
	v_mov_b64_e32 v[98:99], v[34:35]
	v_mov_b64_e32 v[100:101], v[34:35]
	v_mov_b64_e32 v[102:103], v[34:35]
	v_mov_b64_e32 v[104:105], v[34:35]
	v_mov_b64_e32 v[106:107], v[34:35]
	v_mov_b64_e32 v[108:109], v[34:35]
	v_mov_b64_e32 v[110:111], v[34:35]
	v_mov_b64_e32 v[112:113], v[34:35]
	v_mov_b64_e32 v[114:115], v[34:35]
	v_mov_b64_e32 v[116:117], v[34:35]
	v_mov_b64_e32 v[118:119], v[34:35]
	v_mov_b64_e32 v[120:121], v[34:35]
	v_mov_b64_e32 v[122:123], v[34:35]
	v_mov_b64_e32 v[124:125], v[34:35]
	v_mov_b64_e32 v[126:127], v[34:35]
	v_mov_b64_e32 v[128:129], v[34:35]
	v_mov_b64_e32 v[130:131], v[34:35]
	v_mov_b64_e32 v[132:133], v[34:35]
	v_mov_b64_e32 v[134:135], v[34:35]
	v_mov_b64_e32 v[136:137], v[34:35]
	v_mov_b64_e32 v[138:139], v[34:35]
	v_mov_b64_e32 v[140:141], v[34:35]
	v_mov_b64_e32 v[142:143], v[34:35]
	v_mov_b64_e32 v[144:145], v[34:35]
	v_mov_b64_e32 v[146:147], v[34:35]
	v_mov_b64_e32 v[148:149], v[34:35]
	v_mov_b64_e32 v[150:151], v[34:35]
	v_mov_b64_e32 v[152:153], v[34:35]
	v_mov_b64_e32 v[154:155], v[34:35]
	v_mov_b64_e32 v[156:157], v[34:35]
	v_mov_b64_e32 v[158:159], v[34:35]
	v_mov_b64_e32 v[160:161], v[34:35]

; template <int MODE, bool FX>
; DI void attn_compute(const int lane, const bf16_t* Ks, const bf16_t* Vs, const bf16x8 (&qf)[2][2], AttnSt& st, const float (&invl)[2],
;                      int lo, int hi, float (&impA)[4], float (&impE)[4], const float CL) {
;     ...
;       const bf16x8 ones = mk8(0x3F803F80u, 0x3F803F80u, 0x3F803F80u, 0x3F803F80u);
; template <bool FX>
; DI void nsa_tile(const Params& p, int b, int g, int tile, bf16_t* lds, const float CL) {
;     ...
;   for (int hp = 0; hp < 2; ++hp) {
; #pragma unroll
;     for (int hh = 0; hh < 2; ++hh)
; #pragma unroll
;       for (int ks = 0; ks < 2; ++ks) qf[hh][ks] = *(const bf16x8*)(ztok + C_Q + g * 256 + (hp * 2 + hh) * 64 + ks * 32 + quad * 8);
;     st_reset(st);
;     {
;       const bf16_t* kb = zb + C_KS + g * 64;
;       tile64_gload(tid, rk0, rk1, kb, ZS);
;       tile64_gload(tid, rv0, rv1, vsT, TS);
.LBB0_665:
	s_lshl_b32 s28, s6, 8
	v_lshl_add_u64 v[14:15], v[116:117], 0, s[28:29]
	global_load_dwordx4 v[2:5], v[14:15], off
	global_load_dwordx4 v[6:9], v[14:15], off offset:64
	global_load_dwordx4 v[10:13], v[14:15], off offset:128
	s_nop 0
	global_load_dwordx4 v[14:17], v[14:15], off offset:192
	s_nop 0
	v_and_b32_e32 v202, 7, v196
	v_bfe_u32 v218, v196, 4, 3
	v_xor_b32_e32 v202, v202, v218
	v_lshlrev_b32_e32 v202, 4, v202
	v_mov_b32_e32 v203, 0
	v_sub_u32_e32 v218, v202, v0
	v_ashrrev_i32_e32 v219, 31, v218
	v_readfirstlane_b32 s77, v196
	s_lshr_b32 s76, s77, 8
	s_lshl_b32 s76, s76, 16
	s_bfe_u32 s77, s77, 0x20006
	s_lshl_b32 s77, s77, 10
	s_or_b32 s76, s76, s77
	s_or_b32 s76, s76, 0xc000
	s_mov_b32 s75, 0xc000
	s_movk_i32 s78, 0x600
	s_mov_b32 s79, 0
	v_lshl_add_u64 v[58:59], v[132:133], 0, v[218:219]
	v_lshl_add_u64 v[60:61], v[136:137], 0, v[218:219]
	v_lshl_add_u64 v[62:63], v[140:141], 0, v[218:219]
	v_lshl_add_u64 v[64:65], v[144:145], 0, v[218:219]
	v_lshl_add_u64 v[58:59], v[58:59], 0, s[78:79]
	v_lshl_add_u64 v[60:61], v[60:61], 0, s[78:79]
	s_mov_b32 m0, s76
	s_nop 0
	global_load_lds_dwordx4 v[58:59], off
	s_add_u32 m0, s76, 0x1000
	s_nop 0
	global_load_lds_dwordx4 v[60:61], off
	s_add_u32 m0, s76, 0x2000
	s_nop 0
	global_load_lds_dwordx4 v[62:63], off
	s_add_u32 m0, s76, 0x3000
	s_nop 0
	global_load_lds_dwordx4 v[64:65], off
	s_xor_b32 s76, s76, 0xc000
	v_mov_b32_e32 v58, s8
	v_mov_b32_e32 v59, s8
	v_mov_b32_e32 v60, s8
	v_mov_b32_e32 v61, s8
	v_xor_b32_e32 v188, 0xc000, v188
	v_xor_b32_e32 v189, 0xc000, v189
	v_xor_b32_e32 v190, 0xc000, v190
	v_xor_b32_e32 v191, 0xc000, v191
	v_xor_b32_e32 v207, 0xc000, v207
	v_xor_b32_e32 v208, 0xc000, v208
	v_xor_b32_e32 v209, 0xc000, v209
	v_xor_b32_e32 v210, 0xc000, v210
	v_xor_b32_e32 v211, 0xc000, v211
	v_xor_b32_e32 v212, 0xc000, v212
	v_xor_b32_e32 v213, 0xc000, v213
	v_xor_b32_e32 v214, 0xc000, v214
	v_mov_b32_e32 v54, v1
	v_mov_b32_e32 v55, v1
	v_mov_b32_e32 v56, v1
	v_mov_b32_e32 v57, v1
	v_mov_b64_e32 v[46:47], v[54:55]
	v_mov_b64_e32 v[50:51], v[54:55]
	v_mov_b64_e32 v[42:43], v[54:55]
	v_mov_b64_e32 v[38:39], v[54:55]
	v_mov_b64_e32 v[34:35], v[54:55]
	v_mov_b64_e32 v[30:31], v[54:55]
	v_mov_b64_e32 v[26:27], v[54:55]
	v_mov_b64_e32 v[22:23], v[54:55]
	v_mov_b64_e32 v[18:19], v[54:55]
	s_xor_b64 s[36:37], s[2:3], -1
	s_lshl_b32 s7, s6, 7
	s_mov_b32 s28, 64
	s_mov_b32 s68, -1
	v_mov_b32_e32 v187, v185
	v_lshl_add_u64 v[158:159], v[156:157], 0, v[218:219]
	v_lshl_add_u64 v[160:161], v[154:155], 0, v[218:219]
	v_mov_b64_e32 v[48:49], v[56:57]
	v_mov_b64_e32 v[52:53], v[56:57]
	v_mov_b64_e32 v[44:45], v[56:57]
	v_mov_b64_e32 v[40:41], v[56:57]
	v_mov_b64_e32 v[36:37], v[56:57]
	v_mov_b64_e32 v[32:33], v[56:57]
	v_mov_b64_e32 v[28:29], v[56:57]
	v_mov_b64_e32 v[24:25], v[56:57]
	v_mov_b64_e32 v[20:21], v[56:57]
	s_branch .LBB0_668
; template <int MODE, bool FX>
; DI void attn_compute(const int lane, const bf16_t* Ks, const bf16_t* Vs, const bf16x8 (&qf)[2][2], AttnSt& st, const float (&invl)[2],
;                      int lo, int hi, float (&impA)[4], float (&impE)[4], const float CL) {
;     ...
;   for (int ks = 0; ks < 2; ++ks) {
; #pragma unroll
;     for (int kt = 0; kt < 4; ++kt) {
;       int row = kt * 16 + col;
;       bf16x8 kf = *(const bf16x8*)(Ks + row * 64 + (((ks * 4 + quad) ^ ((row >> 1) & 7)) << 3));
; #pragma unroll
;       for (int hh = 0; hh < 2; ++hh) S[kt][hh] = mfma16(kf, qf[hh][ks], S[kt][hh]);
;     }
;   }
;   bf16x8 pf[2][2];
;   const bool full = (lo <= 0) && (hi >= 63);
;   const bool none = (hi < 0) || (lo > 63) || (hi < lo);
;   if (__all(full || none)) {
;     constexpr float L2E = 1.4426950408889634f;
; #pragma unroll
;     for (int hh = 0; hh < 2; ++hh) {
;       float mL;
;       float il = 1.f;
;       if (FX) {
;         mL = full ? CL : 1e30f;
;         if (MODE == 1) il = invl[hh];
;       } else if (MODE != 1) {
;         float mx = -1e30f;
; #pragma unroll
;         for (int kt = 0; kt < 4; ++kt)
; #pragma unroll
;           for (int j = 0; j < 4; ++j) mx = fmaxf(mx, S[kt][hh][j]);
;         mx = full ? mx : -1e30f;
;         mx = fmaxf(mx, shx(mx, 16, lane));
;         mx = fmaxf(mx, shx(mx, 32, lane));
;         const float m_new = fmaxf(st.m[hh], mx);
;         const float alpha = __expf(st.m[hh] - m_new);
;         st.m[hh] = m_new;
;         st.l[hh] *= alpha;
;         if (MODE == 2) {
; #pragma unroll
;           for (int dt = 0; dt < 4; ++dt) st.O[hh][dt] *= alpha;
;         }
;         mL = full ? m_new * L2E : 1e30f;
;       } else {
;         mL = full ? st.m[hh] * L2E : 1e30f;
;         il = invl[hh];
;       }
;       float rs = 0.f;
; #pragma unroll
;       for (int kt = 0; kt < 4; ++kt) {
;         float a = 0.f;
; #pragma unroll
;         for (int j = 0; j < 4; ++j) {
;           float pv = __builtin_amdgcn_exp2f(fmaf(S[kt][hh][j], L2E, -mL));
;           if (MODE == 1) pv *= il;
;           S[kt][hh][j] = pv;
;           a += pv;
;         }
;         rs += a;
;         if (MODE == 1) {
;           impA[kt] += a;
;           impE[kt] += S[kt][hh][3];
;         }
;       }
;       if (MODE != 1 && !(FX && MODE == 2)) st.l[hh] += rs;
;       if (MODE != 0) {
; #pragma unroll
;         for (int c = 0; c < 2; ++c)
.Lnsa_fast:
	s_waitcnt lgkmcnt(7)
	v_mfma_f32_16x16x32_bf16 v[98:101], v[220:223], v[2:5], 0
	s_waitcnt lgkmcnt(6)
	v_mfma_f32_16x16x32_bf16 v[106:109], v[224:227], v[2:5], 0
	s_waitcnt lgkmcnt(5)
	v_mfma_f32_16x16x32_bf16 v[102:105], v[228:231], v[2:5], 0
	s_waitcnt lgkmcnt(4)
	v_mfma_f32_16x16x32_bf16 v[110:113], v[232:235], v[2:5], 0
	s_waitcnt lgkmcnt(3)
	v_mfma_f32_16x16x32_bf16 v[98:101], v[236:239], v[6:9], v[98:101]
	s_waitcnt lgkmcnt(2)
	v_mfma_f32_16x16x32_bf16 v[106:109], v[240:243], v[6:9], v[106:109]
	s_waitcnt lgkmcnt(1)
	v_mfma_f32_16x16x32_bf16 v[102:105], v[244:247], v[6:9], v[102:105]
	s_waitcnt lgkmcnt(0)
	v_mfma_f32_16x16x32_bf16 v[110:113], v[198:201], v[6:9], v[110:113]
	v_cmp_lt_i32_e32 vcc, 62, v215
	v_mfma_f32_16x16x32_bf16 v[90:93], v[220:223], v[10:13], 0
	v_mfma_f32_16x16x32_bf16 v[94:97], v[224:227], v[10:13], 0
	v_cndmask_b32_e32 v217, v197, v205, vcc
	v_mfma_f32_16x16x32_bf16 v[82:85], v[228:231], v[10:13], 0
	v_mfma_f32_16x16x32_bf16 v[86:89], v[232:235], v[10:13], 0
	v_fmamk_f32 v74, v98, 0x3fb8aa3b, v217
	v_fmamk_f32 v75, v99, 0x3fb8aa3b, v217
	v_mfma_f32_16x16x32_bf16 v[90:93], v[236:239], v[14:17], v[90:93]
	v_fmamk_f32 v76, v100, 0x3fb8aa3b, v217
	v_fmamk_f32 v77, v101, 0x3fb8aa3b, v217
	v_mfma_f32_16x16x32_bf16 v[94:97], v[240:243], v[14:17], v[94:97]
	v_fmamk_f32 v78, v106, 0x3fb8aa3b, v217
	v_fmamk_f32 v79, v107, 0x3fb8aa3b, v217
	v_mfma_f32_16x16x32_bf16 v[82:85], v[244:247], v[14:17], v[82:85]
	v_fmamk_f32 v80, v108, 0x3fb8aa3b, v217
	v_fmamk_f32 v81, v109, 0x3fb8aa3b, v217
	v_mfma_f32_16x16x32_bf16 v[86:89], v[198:201], v[14:17], v[86:89]
	ds_read_b64 v[220:221], v207 offset:8192
	v_fmamk_f32 v164, v102, 0x3fb8aa3b, v217
	ds_read_b64 v[222:223], v208 offset:8192
	v_fmamk_f32 v165, v103, 0x3fb8aa3b, v217
	ds_read_b64 v[224:225], v209 offset:8192
	v_fmamk_f32 v166, v104, 0x3fb8aa3b, v217
	ds_read_b64 v[226:227], v210 offset:8192
	v_fmamk_f32 v167, v105, 0x3fb8aa3b, v217
	ds_read_b64 v[228:229], v207 offset:10240
	v_fmamk_f32 v168, v110, 0x3fb8aa3b, v217
	ds_read_b64 v[230:231], v208 offset:10240
	v_fmamk_f32 v169, v111, 0x3fb8aa3b, v217
	ds_read_b64 v[232:233], v209 offset:10240
	v_fmamk_f32 v170, v112, 0x3fb8aa3b, v217
	ds_read_b64 v[234:235], v210 offset:10240
	v_fmamk_f32 v171, v113, 0x3fb8aa3b, v217
	ds_read_b64 v[236:237], v207 offset:12288
	v_exp_f32_e32 v74, v74
	ds_read_b64 v[238:239], v208 offset:12288
	v_exp_f32_e32 v75, v75
	ds_read_b64 v[240:241], v209 offset:12288
	v_exp_f32_e32 v76, v76
	ds_read_b64 v[242:243], v210 offset:12288
	v_exp_f32_e32 v77, v77
	ds_read_b64 v[244:245], v211 offset:8192
	v_exp_f32_e32 v78, v78
	ds_read_b64 v[246:247], v212 offset:8192
	v_exp_f32_e32 v79, v79
	ds_read_b64 v[198:199], v213 offset:8192
	v_exp_f32_e32 v80, v80
	ds_read_b64 v[200:201], v214 offset:8192
	v_exp_f32_e32 v81, v81
	v_exp_f32_e32 v164, v164
	v_exp_f32_e32 v165, v165
	v_exp_f32_e32 v166, v166
	v_exp_f32_e32 v167, v167
	v_exp_f32_e32 v168, v168
	v_exp_f32_e32 v169, v169
	v_exp_f32_e32 v170, v170
	v_exp_f32_e32 v171, v171
	v_cvt_pk_bf16_f32 v74, v74, v75
	v_cvt_pk_bf16_f32 v75, v76, v77
	v_cvt_pk_bf16_f32 v76, v78, v79
	v_cvt_pk_bf16_f32 v77, v80, v81
	v_cvt_pk_bf16_f32 v78, v164, v165
	v_cvt_pk_bf16_f32 v79, v166, v167
	v_cvt_pk_bf16_f32 v80, v168, v169
	v_cvt_pk_bf16_f32 v81, v170, v171
	s_waitcnt lgkmcnt(0)
	v_fmamk_f32 v164, v90, 0x3fb8aa3b, v217
	v_fmamk_f32 v165, v91, 0x3fb8aa3b, v217
	v_fmamk_f32 v166, v92, 0x3fb8aa3b, v217
	v_mfma_f32_16x16x32_bf16 v[50:53], v[220:223], v[74:77], v[50:53]
	v_fmamk_f32 v167, v93, 0x3fb8aa3b, v217
	v_mfma_f32_16x16x32_bf16 v[42:45], v[228:231], v[74:77], v[42:45]
	v_fmamk_f32 v168, v94, 0x3fb8aa3b, v217
	v_fmamk_f32 v169, v95, 0x3fb8aa3b, v217
	v_mfma_f32_16x16x32_bf16 v[38:41], v[236:239], v[74:77], v[38:41]
	v_fmamk_f32 v170, v96, 0x3fb8aa3b, v217
	v_fmamk_f32 v171, v97, 0x3fb8aa3b, v217
	v_fmamk_f32 v172, v82, 0x3fb8aa3b, v217
	v_fmamk_f32 v173, v83, 0x3fb8aa3b, v217
	v_mfma_f32_16x16x32_bf16 v[34:37], v[244:247], v[74:77], v[34:37]
	v_fmamk_f32 v174, v84, 0x3fb8aa3b, v217
	v_fmamk_f32 v175, v85, 0x3fb8aa3b, v217
	v_fmamk_f32 v176, v86, 0x3fb8aa3b, v217
	v_fmamk_f32 v177, v87, 0x3fb8aa3b, v217
	v_mfma_f32_16x16x32_bf16 v[50:53], v[224:227], v[78:81], v[50:53]
	v_fmamk_f32 v178, v88, 0x3fb8aa3b, v217
	v_fmamk_f32 v179, v89, 0x3fb8aa3b, v217
	v_exp_f32_e32 v164, v164
	v_exp_f32_e32 v165, v165
	v_mfma_f32_16x16x32_bf16 v[42:45], v[232:235], v[78:81], v[42:45]
	v_exp_f32_e32 v166, v166
	v_exp_f32_e32 v167, v167
	v_exp_f32_e32 v168, v168
	v_exp_f32_e32 v169, v169
	v_mfma_f32_16x16x32_bf16 v[38:41], v[240:243], v[78:81], v[38:41]
	v_exp_f32_e32 v170, v170
	v_exp_f32_e32 v171, v171
	v_exp_f32_e32 v172, v172
	v_exp_f32_e32 v173, v173
	v_mfma_f32_16x16x32_bf16 v[34:37], v[198:201], v[78:81], v[34:37]
	v_exp_f32_e32 v174, v174
	v_exp_f32_e32 v175, v175
	v_exp_f32_e32 v176, v176
	v_exp_f32_e32 v177, v177
	v_mfma_f32_16x16x32_bf16 v[54:57], v[58:61], v[74:77], v[54:57]
	v_exp_f32_e32 v178, v178
	v_exp_f32_e32 v179, v179
	v_cvt_pk_bf16_f32 v82, v164, v165
	v_cvt_pk_bf16_f32 v83, v166, v167
	v_mfma_f32_16x16x32_bf16 v[54:57], v[58:61], v[78:81], v[54:57]
	v_cvt_pk_bf16_f32 v84, v168, v169
	v_cvt_pk_bf16_f32 v85, v170, v171
	v_cvt_pk_bf16_f32 v86, v172, v173
	v_cvt_pk_bf16_f32 v87, v174, v175
	v_cvt_pk_bf16_f32 v88, v176, v177
	v_cvt_pk_bf16_f32 v89, v178, v179
	s_nop 1
	v_mfma_f32_16x16x32_bf16 v[30:33], v[220:223], v[82:85], v[30:33]
	v_mfma_f32_16x16x32_bf16 v[26:29], v[228:231], v[82:85], v[26:29]
	v_mfma_f32_16x16x32_bf16 v[22:25], v[236:239], v[82:85], v[22:25]
	v_mfma_f32_16x16x32_bf16 v[18:21], v[244:247], v[82:85], v[18:21]
	v_mfma_f32_16x16x32_bf16 v[30:33], v[224:227], v[86:89], v[30:33]
	v_mfma_f32_16x16x32_bf16 v[26:29], v[232:235], v[86:89], v[26:29]
	v_mfma_f32_16x16x32_bf16 v[22:25], v[240:243], v[86:89], v[22:25]
	v_mfma_f32_16x16x32_bf16 v[18:21], v[198:201], v[86:89], v[18:21]
	v_mfma_f32_16x16x32_bf16 v[46:49], v[58:61], v[82:85], v[46:49]
	v_mfma_f32_16x16x32_bf16 v[46:49], v[58:61], v[86:89], v[46:49]
	s_branch .LBB0_667

; DI void zero_acc8(f32x4 (&acc)[8][4]) {
; #pragma unroll
;   for (int i = 0; i < 8; ++i)
; #pragma unroll
;     for (int j = 0; j < 4; ++j) acc[i][j] = f32x4{0.f, 0.f, 0.f, 0.f};
; }
; __global__ void __launch_bounds__(512, 2) mega(Params p) {
;     ...
;     GEMM8_TILE_LOOP(4) {
;       const int m0 = mt * 256, n0 = ntile * 256;
;       f32x4 acc8[8][4];
;       zero_acc8(acc8);
;       gemm8_accum(acc8, (const bf16_t*)(p.ws + O_ONSA) + (size_t)m0 * 512, 512, wl + W_UPA + (size_t)n0 * 512, 512, 8, lds_all, !first_,
;                   z + (size_t)m0 * ZS + C_RQ, ZS, wl + W_UPR + (size_t)n0 * 512, 512);
.LBB0_777:
	v_lshlrev_b64 v[38:39], 1, v[168:169]
	v_lshl_add_u64 v[6:7], s[2:3], 0, v[38:39]
	v_lshlrev_b64 v[40:41], 1, v[166:167]
	v_lshlrev_b64 v[42:43], 1, v[164:165]
	v_lshl_add_u64 v[8:9], s[2:3], 0, v[40:41]
	global_load_dwordx4 v[18:21], v[6:7], off offset:128
	global_load_dwordx4 v[26:29], v[8:9], off offset:128
	v_lshl_add_u64 v[6:7], s[2:3], 0, v[42:43]
	global_load_dwordx4 v[22:25], v[4:5], off offset:128
	global_load_dwordx4 v[30:33], v[6:7], off offset:128
	global_load_dwordx4 v[14:17], v[2:3], off offset:128
	v_lshl_add_u64 v[2:3], s[0:1], 0, v[38:39]
	s_nop 1
	global_load_dwordx4 v[2:5], v[2:3], off offset:128
	v_lshl_add_u64 v[6:7], s[0:1], 0, v[40:41]
	v_lshl_add_u64 v[10:11], s[0:1], 0, v[42:43]
	global_load_dwordx4 v[6:9], v[6:7], off offset:128
	s_nop 0
	global_load_dwordx4 v[10:13], v[10:11], off offset:128
	s_lshl_b32 s7, s11, 10
	v_bfe_u32 v44, v35, 4, 2
	v_lshrrev_b32_e32 v45, 1, v35
	s_and_b32 s21, s7, 0xc0000
	s_and_b32 s7, s10, 0x60
	v_readlane_b32 s20, v252, 25
	v_bitop3_b32 v45, v45, v44, 7 bitop3:0x6c
	s_or_b32 s7, s20, s7
	s_and_b32 s20, s9, 3
	v_lshlrev_b32_e32 v169, 3, v45
	v_lshlrev_b32_e32 v45, 5, v35
	s_add_i32 s7, s7, s20
	v_bfe_u32 v46, v35, 1, 3
	v_and_b32_e32 v45, 0xffffe000, v45
	v_lshlrev_b32_e32 v35, 6, v35
	s_movk_i32 s0, 0x3c0
	s_lshl_b32 s13, s13, 8
	s_lshl_b32 s6, s12, 9
	s_lshl_b32 s20, s7, 18
	v_and_or_b32 v45, v35, s0, v45
	v_and_b32_e32 v47, 0x33c0, v35
	v_bitop3_b32 v35, v44, v46, 4 bitop3:0x36
	v_readlane_b32 s0, v254, 10
	v_lshlrev_b32_e32 v189, 3, v35
	s_add_u32 s0, s0, s21
	v_readlane_b32 s1, v254, 11
	v_add_u32_e32 v34, v34, v170
	v_mov_b32_e32 v35, v1
	s_addc_u32 s1, s1, 0
	v_lshlrev_b64 v[34:35], 1, v[34:35]
	v_lshl_add_u64 v[172:173], s[0:1], 0, v[42:43]
	v_lshl_add_u64 v[174:175], s[0:1], 0, v[40:41]
	v_lshl_add_u64 v[176:177], s[0:1], 0, v[38:39]
	v_lshl_add_u64 v[178:179], s[0:1], 0, v[34:35]
	v_readlane_b32 s0, v254, 14
	s_add_u32 s0, s0, s20
	v_readlane_b32 s1, v254, 15
	s_addc_u32 s1, s1, 0
	v_lshlrev_b32_e32 v165, 1, v37
	v_lshlrev_b32_e32 v167, 1, v36
	v_lshl_add_u64 v[186:187], s[0:1], 0, v[34:35]
	v_mov_b32_e32 v34, 0
	v_add3_u32 v163, 0, v165, v167
	v_lshl_add_u64 v[180:181], s[0:1], 0, v[42:43]
	v_lshl_add_u64 v[182:183], s[0:1], 0, v[40:41]
	v_lshl_add_u64 v[184:185], s[0:1], 0, v[38:39]
	s_mov_b64 s[0:1], 0
	s_mov_b32 s2, 0
	v_lshlrev_b32_e32 v188, 1, v45
	v_lshlrev_b32_e32 v171, 1, v47
	v_mov_b32_e32 v35, v34
	v_mov_b64_e32 v[36:37], v[34:35]
	v_mov_b64_e32 v[38:39], v[34:35]
	v_mov_b64_e32 v[40:41], v[34:35]
	v_mov_b64_e32 v[42:43], v[34:35]
	v_mov_b64_e32 v[44:45], v[34:35]
	v_mov_b64_e32 v[46:47], v[34:35]
	v_mov_b64_e32 v[48:49], v[34:35]
	v_mov_b64_e32 v[50:51], v[34:35]
	v_mov_b64_e32 v[52:53], v[34:35]
	v_mov_b64_e32 v[54:55], v[34:35]
	v_mov_b64_e32 v[56:57], v[34:35]
	v_mov_b64_e32 v[58:59], v[34:35]
	v_mov_b64_e32 v[60:61], v[34:35]
	v_mov_b64_e32 v[62:63], v[34:35]
	v_mov_b64_e32 v[64:65], v[34:35]
	v_mov_b64_e32 v[66:67], v[34:35]
	v_mov_b64_e32 v[68:69], v[34:35]
	v_mov_b64_e32 v[70:71], v[34:35]
	v_mov_b64_e32 v[72:73], v[34:35]
	v_mov_b64_e32 v[74:75], v[34:35]
	v_mov_b64_e32 v[76:77], v[34:35]
	v_mov_b64_e32 v[78:79], v[34:35]
	v_mov_b64_e32 v[80:81], v[34:35]
	v_mov_b64_e32 v[82:83], v[34:35]
	v_mov_b64_e32 v[84:85], v[34:35]
	v_mov_b64_e32 v[86:87], v[34:35]
	v_mov_b64_e32 v[88:89], v[34:35]
	v_mov_b64_e32 v[90:91], v[34:35]
	v_mov_b64_e32 v[92:93], v[34:35]
	v_mov_b64_e32 v[94:95], v[34:35]
	v_mov_b64_e32 v[96:97], v[34:35]
	v_mov_b64_e32 v[98:99], v[34:35]
	v_mov_b64_e32 v[100:101], v[34:35]
	v_mov_b64_e32 v[102:103], v[34:35]
	v_mov_b64_e32 v[104:105], v[34:35]
	v_mov_b64_e32 v[106:107], v[34:35]
	v_mov_b64_e32 v[108:109], v[34:35]
	v_mov_b64_e32 v[110:111], v[34:35]
	v_mov_b64_e32 v[112:113], v[34:35]
	v_mov_b64_e32 v[114:115], v[34:35]
	v_mov_b64_e32 v[116:117], v[34:35]
	v_mov_b64_e32 v[118:119], v[34:35]
	v_mov_b64_e32 v[120:121], v[34:35]
	v_mov_b64_e32 v[122:123], v[34:35]
	v_mov_b64_e32 v[124:125], v[34:35]
	v_mov_b64_e32 v[126:127], v[34:35]
	v_mov_b64_e32 v[128:129], v[34:35]
	v_mov_b64_e32 v[130:131], v[34:35]
	v_mov_b64_e32 v[132:133], v[34:35]
	v_mov_b64_e32 v[134:135], v[34:35]
	v_mov_b64_e32 v[136:137], v[34:35]
	v_mov_b64_e32 v[138:139], v[34:35]
	v_mov_b64_e32 v[140:141], v[34:35]
	v_mov_b64_e32 v[142:143], v[34:35]
	v_mov_b64_e32 v[144:145], v[34:35]
	v_mov_b64_e32 v[146:147], v[34:35]
	v_mov_b64_e32 v[148:149], v[34:35]
	v_mov_b64_e32 v[150:151], v[34:35]
	v_mov_b64_e32 v[152:153], v[34:35]
	v_mov_b64_e32 v[154:155], v[34:35]
	v_mov_b64_e32 v[156:157], v[34:35]
	v_mov_b64_e32 v[158:159], v[34:35]
	v_mov_b64_e32 v[160:161], v[34:35]

; DI void zero_acc8(f32x4 (&acc)[8][4]) {
; #pragma unroll
;   for (int i = 0; i < 8; ++i)
; #pragma unroll
;     for (int j = 0; j < 4; ++j) acc[i][j] = f32x4{0.f, 0.f, 0.f, 0.f};
; }
; __global__ void __launch_bounds__(512, 2) mega(Params p) {
;     ...
;     GEMM8_TILE_LOOP(4) {
;       const int m0 = mt * 256, n0 = ntile * 256;
;       f32x4 acc8[8][4];
;       zero_acc8(acc8);
;       gemm8_accum(acc8, z + (size_t)m0 * ZS + C_RK, ZS, wl + W_OUT + (size_t)n0 * 1024, 1024, 16, lds_all, !first_,
;                   z + (size_t)mtn * 256 * ZS + C_RK, ZS, wl + W_OUT + (size_t)ntilen * 256 * 1024, 1024);
;       gemm8_epi_resid(acc8, m0, n0, ntile, lds_all, xin, p.out, hbuf, rowpart);
.LBB0_829:
	v_lshlrev_b64 v[38:39], 1, v[0:1]
	v_lshlrev_b64 v[40:41], 1, v[176:177]
	v_lshl_add_u64 v[2:3], s[2:3], 0, v[38:39]
	v_lshl_add_u64 v[4:5], s[2:3], 0, v[40:41]
	v_lshlrev_b64 v[42:43], 1, v[174:175]
	v_lshlrev_b64 v[44:45], 1, v[172:173]
	global_load_dwordx4 v[18:21], v[2:3], off offset:3760
	global_load_dwordx4 v[22:25], v[4:5], off offset:3760
	v_lshl_add_u64 v[2:3], s[2:3], 0, v[42:43]
	v_lshl_add_u64 v[4:5], s[2:3], 0, v[44:45]
	v_lshlrev_b64 v[46:47], 1, v[170:171]
	v_lshlrev_b64 v[48:49], 1, v[168:169]
	v_lshlrev_b64 v[50:51], 1, v[166:167]
	v_lshlrev_b64 v[52:53], 1, v[164:165]
	global_load_dwordx4 v[26:29], v[2:3], off offset:3760
	global_load_dwordx4 v[30:33], v[4:5], off offset:3760
	v_lshl_add_u64 v[2:3], s[0:1], 0, v[46:47]
	v_lshl_add_u64 v[4:5], s[0:1], 0, v[48:49]
	v_lshl_add_u64 v[6:7], s[0:1], 0, v[50:51]
	v_lshl_add_u64 v[10:11], s[0:1], 0, v[52:53]
	global_load_dwordx4 v[14:17], v[2:3], off offset:128
	s_nop 0
	global_load_dwordx4 v[2:5], v[4:5], off offset:128
	s_nop 0
	global_load_dwordx4 v[6:9], v[6:7], off offset:128
	s_nop 0
	global_load_dwordx4 v[10:13], v[10:11], off offset:128
	v_bfe_u32 v37, v34, 4, 2
	v_lshrrev_b32_e32 v54, 1, v34
	v_bitop3_b32 v54, v54, v37, 7 bitop3:0x6c
	s_lshr_b32 s7, s13, 2
	s_lshl_b32 s6, s12, 8
	s_and_b32 s12, s10, 0x60
	v_readlane_b32 s20, v252, 25
	v_lshlrev_b32_e32 v169, 3, v54
	v_lshlrev_b32_e32 v54, 5, v34
	s_and_b32 s7, s7, 3
	s_or_b32 s12, s20, s12
	s_and_b32 s20, s9, 3
	v_bfe_u32 v55, v34, 1, 3
	v_and_b32_e32 v54, 0xffffe000, v54
	v_lshlrev_b32_e32 v34, 6, v34
	s_movk_i32 s0, 0x3c0
	s_lshl_b32 s7, s7, 19
	s_add_i32 s12, s12, s20
	v_and_or_b32 v54, v34, s0, v54
	v_readlane_b32 s0, v254, 24
	s_add_u32 s0, s0, s7
	v_readlane_b32 s1, v254, 25
	s_addc_u32 s1, s1, 0
	s_mul_i32 s12, s12, 0x2a3000
	v_lshl_add_u64 v[178:179], s[0:1], 0, v[52:53]
	v_lshl_add_u64 v[180:181], s[0:1], 0, v[50:51]
	v_lshl_add_u64 v[182:183], s[0:1], 0, v[48:49]
	v_lshl_add_u64 v[184:185], s[0:1], 0, v[46:47]
	v_readlane_b32 s0, v254, 26
	v_and_b32_e32 v56, 0x33c0, v34
	v_bitop3_b32 v34, v37, v55, 4 bitop3:0x36
	s_add_u32 s0, s0, s12
	v_readlane_b32 s1, v254, 27
	v_lshlrev_b32_e32 v205, 3, v34
	v_lshlrev_b32_e32 v165, 1, v36
	v_lshlrev_b32_e32 v167, 1, v35
	s_addc_u32 s1, s1, 0
	v_mov_b32_e32 v34, 0
	v_add3_u32 v163, 0, v165, v167
	v_lshl_add_u64 v[186:187], s[0:1], 0, v[44:45]
	v_lshl_add_u64 v[188:189], s[0:1], 0, v[42:43]
	v_lshl_add_u64 v[190:191], s[0:1], 0, v[40:41]
	v_lshl_add_u64 v[192:193], s[0:1], 0, v[38:39]
	s_mov_b64 s[0:1], 0
	s_mov_b32 s2, 0
	v_lshlrev_b32_e32 v195, 1, v54
	v_lshlrev_b32_e32 v194, 1, v56
	v_mov_b32_e32 v35, v34
	v_mov_b64_e32 v[36:37], v[34:35]
	v_mov_b64_e32 v[38:39], v[34:35]
	v_mov_b64_e32 v[40:41], v[34:35]
	v_mov_b64_e32 v[42:43], v[34:35]
	v_mov_b64_e32 v[44:45], v[34:35]
	v_mov_b64_e32 v[46:47], v[34:35]
	v_mov_b64_e32 v[48:49], v[34:35]
	v_mov_b64_e32 v[50:51], v[34:35]
	v_mov_b64_e32 v[52:53], v[34:35]
	v_mov_b64_e32 v[54:55], v[34:35]
	v_mov_b64_e32 v[56:57], v[34:35]
	v_mov_b64_e32 v[58:59], v[34:35]
	v_mov_b64_e32 v[60:61], v[34:35]
	v_mov_b64_e32 v[62:63], v[34:35]
	v_mov_b64_e32 v[64:65], v[34:35]
	v_mov_b64_e32 v[66:67], v[34:35]
	v_mov_b64_e32 v[68:69], v[34:35]
	v_mov_b64_e32 v[70:71], v[34:35]
	v_mov_b64_e32 v[72:73], v[34:35]
	v_mov_b64_e32 v[74:75], v[34:35]
	v_mov_b64_e32 v[76:77], v[34:35]
	v_mov_b64_e32 v[78:79], v[34:35]
	v_mov_b64_e32 v[80:81], v[34:35]
	v_mov_b64_e32 v[82:83], v[34:35]
	v_mov_b64_e32 v[84:85], v[34:35]
	v_mov_b64_e32 v[86:87], v[34:35]
	v_mov_b64_e32 v[88:89], v[34:35]
	v_mov_b64_e32 v[90:91], v[34:35]
	v_mov_b64_e32 v[92:93], v[34:35]
	v_mov_b64_e32 v[94:95], v[34:35]
	v_mov_b64_e32 v[96:97], v[34:35]
	v_mov_b64_e32 v[98:99], v[34:35]
	v_mov_b64_e32 v[100:101], v[34:35]
	v_mov_b64_e32 v[102:103], v[34:35]
	v_mov_b64_e32 v[104:105], v[34:35]
	v_mov_b64_e32 v[106:107], v[34:35]
	v_mov_b64_e32 v[108:109], v[34:35]
	v_mov_b64_e32 v[110:111], v[34:35]
	v_mov_b64_e32 v[112:113], v[34:35]
	v_mov_b64_e32 v[114:115], v[34:35]
	v_mov_b64_e32 v[116:117], v[34:35]
	v_mov_b64_e32 v[118:119], v[34:35]
	v_mov_b64_e32 v[120:121], v[34:35]
	v_mov_b64_e32 v[122:123], v[34:35]
	v_mov_b64_e32 v[124:125], v[34:35]
	v_mov_b64_e32 v[126:127], v[34:35]
	v_mov_b64_e32 v[128:129], v[34:35]
	v_mov_b64_e32 v[130:131], v[34:35]
	v_mov_b64_e32 v[132:133], v[34:35]
	v_mov_b64_e32 v[134:135], v[34:35]
	v_mov_b64_e32 v[136:137], v[34:35]
	v_mov_b64_e32 v[138:139], v[34:35]
	v_mov_b64_e32 v[140:141], v[34:35]
	v_mov_b64_e32 v[142:143], v[34:35]
	v_mov_b64_e32 v[144:145], v[34:35]
	v_mov_b64_e32 v[146:147], v[34:35]
	v_mov_b64_e32 v[148:149], v[34:35]
	v_mov_b64_e32 v[150:151], v[34:35]
	v_mov_b64_e32 v[152:153], v[34:35]
	v_mov_b64_e32 v[154:155], v[34:35]
	v_mov_b64_e32 v[156:157], v[34:35]
	v_mov_b64_e32 v[158:159], v[34:35]
	v_mov_b64_e32 v[160:161], v[34:35]

; DI void zero_acc8(f32x4 (&acc)[8][4]) {
; #pragma unroll
;   for (int i = 0; i < 8; ++i)
; #pragma unroll
;     for (int j = 0; j < 4; ++j) acc[i][j] = f32x4{0.f, 0.f, 0.f, 0.f};
; }
; __global__ void __launch_bounds__(512, 2) mega(Params p) {
;     ...
;     GEMM8_TILE_LOOP(16) {
;       const int m0 = mt * 256, n0 = ntile * 256;
;       f32x4 acc8[8][4];
;       zero_acc8(acc8);
;       gemm8_accum(acc8, hbuf + (size_t)m0 * DM, DM, wl + W_FF1 + (size_t)n0 * 1024, 1024, 16, lds_all, !first_,
;                   hbuf + (size_t)mtn * 256 * DM, DM, wl + W_FF1 + (size_t)ntilen * 256 * 1024, 1024);
.LBB0_891:
	v_lshlrev_b64 v[40:41], 1, v[168:169]
	v_lshl_add_u64 v[6:7], s[2:3], 0, v[40:41]
	v_lshlrev_b64 v[42:43], 1, v[166:167]
	v_lshlrev_b64 v[44:45], 1, v[0:1]
	v_lshl_add_u64 v[8:9], s[2:3], 0, v[42:43]
	global_load_dwordx4 v[18:21], v[6:7], off offset:128
	global_load_dwordx4 v[26:29], v[8:9], off offset:128
	v_lshl_add_u64 v[6:7], s[2:3], 0, v[44:45]
	global_load_dwordx4 v[22:25], v[4:5], off offset:128
	global_load_dwordx4 v[30:33], v[6:7], off offset:128
	global_load_dwordx4 v[14:17], v[2:3], off offset:128
	v_lshl_add_u64 v[2:3], s[0:1], 0, v[40:41]
	s_nop 1
	global_load_dwordx4 v[2:5], v[2:3], off offset:128
	v_lshl_add_u64 v[6:7], s[0:1], 0, v[42:43]
	v_lshl_add_u64 v[10:11], s[0:1], 0, v[44:45]
	global_load_dwordx4 v[6:9], v[6:7], off offset:128
	s_nop 0
	global_load_dwordx4 v[10:13], v[10:11], off offset:128
	v_bfe_u32 v39, v36, 4, 2
	v_lshrrev_b32_e32 v46, 1, v36
	v_readlane_b32 s7, v252, 25
	v_bitop3_b32 v46, v46, v39, 7 bitop3:0x6c
	s_or_b32 s7, s7, s12
	s_and_b32 s12, s9, 3
	v_lshlrev_b32_e32 v191, 3, v46
	v_lshlrev_b32_e32 v46, 5, v36
	s_lshl_b32 s6, s10, 11
	s_add_i32 s7, s7, s12
	v_bfe_u32 v47, v36, 1, 3
	v_and_b32_e32 v46, 0xffffe000, v46
	v_lshlrev_b32_e32 v36, 6, v36
	s_movk_i32 s0, 0x3c0
	s_and_b32 s6, s6, 0x780000
	s_lshl_b32 s7, s7, 19
	v_and_or_b32 v46, v36, s0, v46
	v_readlane_b32 s0, v254, 28
	s_add_u32 s0, s0, s6
	v_readlane_b32 s1, v254, 29
	v_add_u32_e32 v34, v35, v34
	v_mov_b32_e32 v35, v1
	s_addc_u32 s1, s1, 0
	v_lshlrev_b64 v[34:35], 1, v[34:35]
	v_lshl_add_u64 v[170:171], s[0:1], 0, v[44:45]
	v_lshl_add_u64 v[172:173], s[0:1], 0, v[42:43]
	v_lshl_add_u64 v[174:175], s[0:1], 0, v[40:41]
	v_lshl_add_u64 v[176:177], s[0:1], 0, v[34:35]
	v_readlane_b32 s0, v253, 57
	s_add_u32 s0, s0, s7
	v_readlane_b32 s1, v253, 58
	s_addc_u32 s1, s1, 0
	v_and_b32_e32 v36, 0x33c0, v36
	v_bitop3_b32 v39, v39, v47, 4 bitop3:0x36
	v_lshlrev_b32_e32 v189, 1, v38
	v_lshlrev_b32_e32 v190, 1, v37
	v_lshl_add_u64 v[184:185], s[0:1], 0, v[34:35]
	v_mov_b32_e32 v34, 0
	v_lshlrev_b32_e32 v188, 3, v39
	v_add3_u32 v163, 0, v189, v190
	v_lshl_add_u64 v[178:179], s[0:1], 0, v[44:45]
	v_lshl_add_u64 v[180:181], s[0:1], 0, v[42:43]
	v_lshl_add_u64 v[182:183], s[0:1], 0, v[40:41]
	s_mov_b64 s[0:1], 0
	s_mov_b32 s2, 0
	v_lshlrev_b32_e32 v187, 1, v46
	v_lshlrev_b32_e32 v186, 1, v36
	v_mov_b32_e32 v35, v34
	v_mov_b64_e32 v[36:37], v[34:35]
	v_mov_b64_e32 v[38:39], v[34:35]
	v_mov_b64_e32 v[40:41], v[34:35]
	v_mov_b64_e32 v[42:43], v[34:35]
	v_mov_b64_e32 v[44:45], v[34:35]
	v_mov_b64_e32 v[46:47], v[34:35]
	v_mov_b64_e32 v[48:49], v[34:35]
	v_mov_b64_e32 v[50:51], v[34:35]
	v_mov_b64_e32 v[52:53], v[34:35]
	v_mov_b64_e32 v[54:55], v[34:35]
	v_mov_b64_e32 v[56:57], v[34:35]
	v_mov_b64_e32 v[58:59], v[34:35]
	v_mov_b64_e32 v[60:61], v[34:35]
	v_mov_b64_e32 v[62:63], v[34:35]
	v_mov_b64_e32 v[64:65], v[34:35]
	v_mov_b64_e32 v[66:67], v[34:35]
	v_mov_b64_e32 v[68:69], v[34:35]
	v_mov_b64_e32 v[70:71], v[34:35]
	v_mov_b64_e32 v[72:73], v[34:35]
	v_mov_b64_e32 v[74:75], v[34:35]
	v_mov_b64_e32 v[76:77], v[34:35]
	v_mov_b64_e32 v[78:79], v[34:35]
	v_mov_b64_e32 v[80:81], v[34:35]
	v_mov_b64_e32 v[82:83], v[34:35]
	v_mov_b64_e32 v[84:85], v[34:35]
	v_mov_b64_e32 v[86:87], v[34:35]
	v_mov_b64_e32 v[88:89], v[34:35]
	v_mov_b64_e32 v[90:91], v[34:35]
	v_mov_b64_e32 v[92:93], v[34:35]
	v_mov_b64_e32 v[94:95], v[34:35]
	v_mov_b64_e32 v[96:97], v[34:35]
	v_mov_b64_e32 v[98:99], v[34:35]
	v_mov_b64_e32 v[100:101], v[34:35]
	v_mov_b64_e32 v[102:103], v[34:35]
	v_mov_b64_e32 v[104:105], v[34:35]
	v_mov_b64_e32 v[106:107], v[34:35]
	v_mov_b64_e32 v[108:109], v[34:35]
	v_mov_b64_e32 v[110:111], v[34:35]
	v_mov_b64_e32 v[112:113], v[34:35]
	v_mov_b64_e32 v[114:115], v[34:35]
	v_mov_b64_e32 v[116:117], v[34:35]
	v_mov_b64_e32 v[118:119], v[34:35]
	v_mov_b64_e32 v[120:121], v[34:35]
	v_mov_b64_e32 v[122:123], v[34:35]
	v_mov_b64_e32 v[124:125], v[34:35]
	v_mov_b64_e32 v[126:127], v[34:35]
	v_mov_b64_e32 v[128:129], v[34:35]
	v_mov_b64_e32 v[130:131], v[34:35]
	v_mov_b64_e32 v[132:133], v[34:35]
	v_mov_b64_e32 v[134:135], v[34:35]
	v_mov_b64_e32 v[136:137], v[34:35]
	v_mov_b64_e32 v[138:139], v[34:35]
	v_mov_b64_e32 v[140:141], v[34:35]
	v_mov_b64_e32 v[142:143], v[34:35]
	v_mov_b64_e32 v[144:145], v[34:35]
	v_mov_b64_e32 v[146:147], v[34:35]
	v_mov_b64_e32 v[148:149], v[34:35]
	v_mov_b64_e32 v[150:151], v[34:35]
	v_mov_b64_e32 v[152:153], v[34:35]
	v_mov_b64_e32 v[154:155], v[34:35]
	v_mov_b64_e32 v[156:157], v[34:35]
	v_mov_b64_e32 v[158:159], v[34:35]
	v_mov_b64_e32 v[160:161], v[34:35]

; DI int TID8() { int t = threadIdx.x; asm volatile("" : "+v"(t)); return t; }
; DI void gemm8_accum(f32x4 (&acc)[8][4], const bf16_t* a, size_t lda, const bf16_t* b, size_t ldb, int nkb, bf16_t* L,
;                     const bool pre, const bf16_t* an, size_t ldan, const bf16_t* bn, size_t ldbn) {
;   const int tid = TID8(), lane = tid & 63, w = tid >> 6;
;   const int wm = w >> 2, wn = w & 3;
;   const int lrow = tid >> 3, lch = tid & 7;
;   u32x4 ra[4], rb[4];
;   unsigned offa[4], offb[4];
; #pragma unroll
;   for (int i = 0; i < 4; ++i) {
;     offa[i] = (unsigned)(lrow + 64 * i) * (unsigned)lda + (unsigned)(lch * 8);
;     offb[i] = (unsigned)(lrow + 64 * i) * (unsigned)ldb + (unsigned)(lch * 8);
;   }
;   if (!pre) {
;     g8_load1o(ra, a, offa);
;     g8_load1o(rb, b, offb);
;     __syncthreads();
;     g8_store(L, ra, rb, lrow, lch);
;   }
;   g8_load1o(ra, a + 64, offa);
;   g8_load1o(rb, b + 64, offb);
; DI void zero_acc8(f32x4 (&acc)[8][4]) {
; #pragma unroll
;   for (int i = 0; i < 8; ++i)
; #pragma unroll
;     for (int j = 0; j < 4; ++j) acc[i][j] = f32x4{0.f, 0.f, 0.f, 0.f};
; }
.LBB0_941:
	v_lshlrev_b64 v[40:41], 1, v[168:169]
	v_lshl_add_u64 v[6:7], s[2:3], 0, v[40:41]
	v_lshlrev_b64 v[42:43], 1, v[166:167]
	v_lshlrev_b64 v[44:45], 1, v[0:1]
	v_lshl_add_u64 v[8:9], s[2:3], 0, v[42:43]
	global_load_dwordx4 v[18:21], v[6:7], off offset:128
	global_load_dwordx4 v[26:29], v[8:9], off offset:128
	v_lshl_add_u64 v[6:7], s[2:3], 0, v[44:45]
	global_load_dwordx4 v[22:25], v[4:5], off offset:128
	global_load_dwordx4 v[30:33], v[6:7], off offset:128
	global_load_dwordx4 v[14:17], v[2:3], off offset:128
	v_lshl_add_u64 v[2:3], s[0:1], 0, v[40:41]
	s_nop 1
	global_load_dwordx4 v[2:5], v[2:3], off offset:128
	v_lshl_add_u64 v[6:7], s[0:1], 0, v[42:43]
	v_lshl_add_u64 v[10:11], s[0:1], 0, v[44:45]
	global_load_dwordx4 v[6:9], v[6:7], off offset:128
	s_nop 0
	global_load_dwordx4 v[10:13], v[10:11], off offset:128
	v_bfe_u32 v39, v36, 4, 2
	v_lshrrev_b32_e32 v46, 1, v36
	s_lshl_b32 s6, s12, 8
	s_and_b32 s12, s10, 0x60
	v_readlane_b32 s20, v252, 25
	v_bitop3_b32 v46, v46, v39, 7 bitop3:0x6c
	s_lshr_b32 s7, s13, 2
	s_or_b32 s12, s20, s12
	s_and_b32 s20, s9, 3
	v_lshlrev_b32_e32 v191, 3, v46
	v_lshlrev_b32_e32 v46, 5, v36
	s_and_b32 s7, s7, 3
	s_add_i32 s12, s12, s20
	v_bfe_u32 v47, v36, 1, 3
	v_and_b32_e32 v46, 0xffffe000, v46
	v_lshlrev_b32_e32 v36, 6, v36
	s_movk_i32 s0, 0x3c0
	s_lshl_b32 s7, s7, 21
	s_lshl_b32 s12, s12, 21
	v_and_or_b32 v46, v36, s0, v46
	v_readlane_b32 s0, v254, 30
	s_add_u32 s0, s0, s7
	v_readlane_b32 s1, v254, 31
	v_add_u32_e32 v34, v35, v34
	v_mov_b32_e32 v35, v1
	s_addc_u32 s1, s1, 0
	v_lshlrev_b64 v[34:35], 1, v[34:35]
	v_lshl_add_u64 v[170:171], s[0:1], 0, v[44:45]
	v_lshl_add_u64 v[172:173], s[0:1], 0, v[42:43]
	v_lshl_add_u64 v[174:175], s[0:1], 0, v[40:41]
	v_lshl_add_u64 v[176:177], s[0:1], 0, v[34:35]
	v_readlane_b32 s0, v254, 32
	s_add_u32 s0, s0, s12
	v_readlane_b32 s1, v254, 33
	s_addc_u32 s1, s1, 0
	v_and_b32_e32 v36, 0x33c0, v36
	v_bitop3_b32 v39, v39, v47, 4 bitop3:0x36
	v_lshlrev_b32_e32 v189, 1, v38
	v_lshlrev_b32_e32 v190, 1, v37
	v_lshl_add_u64 v[184:185], s[0:1], 0, v[34:35]
	v_mov_b32_e32 v34, 0
	v_lshlrev_b32_e32 v188, 3, v39
	v_add3_u32 v163, 0, v189, v190
	v_lshl_add_u64 v[178:179], s[0:1], 0, v[44:45]
	v_lshl_add_u64 v[180:181], s[0:1], 0, v[42:43]
	v_lshl_add_u64 v[182:183], s[0:1], 0, v[40:41]
	s_mov_b64 s[0:1], 0
	s_mov_b32 s2, 0
	v_lshlrev_b32_e32 v187, 1, v46
	v_lshlrev_b32_e32 v186, 1, v36
	v_mov_b32_e32 v35, v34
	v_mov_b64_e32 v[36:37], v[34:35]
	v_mov_b64_e32 v[38:39], v[34:35]
	v_mov_b64_e32 v[40:41], v[34:35]
	v_mov_b64_e32 v[42:43], v[34:35]
	v_mov_b64_e32 v[44:45], v[34:35]
	v_mov_b64_e32 v[46:47], v[34:35]
	v_mov_b64_e32 v[48:49], v[34:35]
	v_mov_b64_e32 v[50:51], v[34:35]
	v_mov_b64_e32 v[52:53], v[34:35]
	v_mov_b64_e32 v[54:55], v[34:35]
	v_mov_b64_e32 v[56:57], v[34:35]
	v_mov_b64_e32 v[58:59], v[34:35]
	v_mov_b64_e32 v[60:61], v[34:35]
	v_mov_b64_e32 v[62:63], v[34:35]
	v_mov_b64_e32 v[64:65], v[34:35]
	v_mov_b64_e32 v[66:67], v[34:35]
	v_mov_b64_e32 v[68:69], v[34:35]
	v_mov_b64_e32 v[70:71], v[34:35]
	v_mov_b64_e32 v[72:73], v[34:35]
	v_mov_b64_e32 v[74:75], v[34:35]
	v_mov_b64_e32 v[76:77], v[34:35]
	v_mov_b64_e32 v[78:79], v[34:35]
	v_mov_b64_e32 v[80:81], v[34:35]
	v_mov_b64_e32 v[82:83], v[34:35]
	v_mov_b64_e32 v[84:85], v[34:35]
	v_mov_b64_e32 v[86:87], v[34:35]
	v_mov_b64_e32 v[88:89], v[34:35]
	v_mov_b64_e32 v[90:91], v[34:35]
	v_mov_b64_e32 v[92:93], v[34:35]
	v_mov_b64_e32 v[94:95], v[34:35]
	v_mov_b64_e32 v[96:97], v[34:35]
	v_mov_b64_e32 v[98:99], v[34:35]
	v_mov_b64_e32 v[100:101], v[34:35]
	v_mov_b64_e32 v[102:103], v[34:35]
	v_mov_b64_e32 v[104:105], v[34:35]
	v_mov_b64_e32 v[106:107], v[34:35]
	v_mov_b64_e32 v[108:109], v[34:35]
	v_mov_b64_e32 v[110:111], v[34:35]
	v_mov_b64_e32 v[112:113], v[34:35]
	v_mov_b64_e32 v[114:115], v[34:35]
	v_mov_b64_e32 v[116:117], v[34:35]
	v_mov_b64_e32 v[118:119], v[34:35]
	v_mov_b64_e32 v[120:121], v[34:35]
	v_mov_b64_e32 v[122:123], v[34:35]
	v_mov_b64_e32 v[124:125], v[34:35]
	v_mov_b64_e32 v[126:127], v[34:35]
	v_mov_b64_e32 v[128:129], v[34:35]
	v_mov_b64_e32 v[130:131], v[34:35]
	v_mov_b64_e32 v[132:133], v[34:35]
	v_mov_b64_e32 v[134:135], v[34:35]
	v_mov_b64_e32 v[136:137], v[34:35]
	v_mov_b64_e32 v[138:139], v[34:35]
	v_mov_b64_e32 v[140:141], v[34:35]
	v_mov_b64_e32 v[142:143], v[34:35]
	v_mov_b64_e32 v[144:145], v[34:35]
	v_mov_b64_e32 v[146:147], v[34:35]
	v_mov_b64_e32 v[148:149], v[34:35]
	v_mov_b64_e32 v[150:151], v[34:35]
	v_mov_b64_e32 v[152:153], v[34:35]
	v_mov_b64_e32 v[154:155], v[34:35]
	v_mov_b64_e32 v[156:157], v[34:35]
	v_mov_b64_e32 v[158:159], v[34:35]
	v_mov_b64_e32 v[160:161], v[34:35]
